# stack + P10: Q rows waited once before the LDS barrier; later waits no longer drain the next unit K/V prefetch
# baseline (speedup 1.0000x reference)
.LBB0_847:
	ds_read_b128 v[32:35], v239 offset:18432
	ds_read_b128 v[48:51], v239 offset:18464
	ds_read_b128 v[52:55], v239 offset:18496
	ds_read_b128 v[56:59], v239 offset:18528
	v_cmp_lt_i32_e32 vcc, v243, v244
	s_waitcnt lgkmcnt(3)
	v_mfma_f32_32x32x16_bf16 v[32:47], v[32:35], v[128:131], 0
	v_add_u32_e32 v132, s86, v164
	s_add_i32 s33, s33, s83
	s_waitcnt lgkmcnt(2)
	v_mfma_f32_32x32x16_bf16 v[32:47], v[48:51], v[124:127], v[32:47]
	s_waitcnt lgkmcnt(1)
	v_mfma_f32_32x32x16_bf16 v[32:47], v[52:55], v[116:119], v[32:47]
	s_waitcnt lgkmcnt(0)
	v_mfma_f32_32x32x16_bf16 v[32:47], v[56:59], v[120:123], v[32:47]
	ds_read_b128 v[60:63], v216
	ds_read_b128 v[56:59], v216 offset:25088
	ds_read_b128 v[48:51], v217
	ds_read_b128 v[52:55], v217 offset:25088
	s_nop 7
	v_cndmask_b32_e64 v116, v32, v240, s[46:47]
	v_cndmask_b32_e64 v116, v116, v32, s[4:5]
	v_cndmask_b32_e64 v117, v240, v33, s[4:5]
	v_cndmask_b32_e64 v34, v34, v240, s[48:49]
	v_cndmask_b32_e64 v35, v35, v240, s[50:51]
	v_max3_f32 v32, v116, s84, v117
	v_cndmask_b32_e64 v36, v36, v240, s[52:53]
	v_cndmask_b32_e64 v37, v37, v240, s[54:55]
	v_max3_f32 v32, v32, v34, v35
	v_cndmask_b32_e64 v38, v38, v240, s[56:57]
	v_cndmask_b32_e64 v39, v39, v240, s[58:59]
	v_max3_f32 v32, v32, v36, v37
	v_cndmask_b32_e64 v40, v40, v240, s[60:61]
	v_cndmask_b32_e64 v41, v41, v240, s[62:63]
	v_max3_f32 v32, v32, v38, v39
	v_cndmask_b32_e64 v42, v42, v240, s[64:65]
	v_cndmask_b32_e64 v43, v43, v240, s[66:67]
	v_max3_f32 v32, v32, v40, v41
	v_cndmask_b32_e64 v44, v44, v240, s[68:69]
	v_cndmask_b32_e64 v45, v45, v240, s[70:71]
	v_max3_f32 v32, v32, v42, v43
	v_cndmask_b32_e64 v46, v46, v240, s[72:73]
	v_cndmask_b32_e64 v47, v47, v240, s[74:75]
	v_max3_f32 v32, v32, v44, v45
	v_cndmask_b32_e32 v33, v133, v243, vcc
	v_max3_f32 v32, v32, v46, v47
	v_lshlrev_b32_e32 v118, 2, v33
	ds_bpermute_b32 v33, v118, v32
	s_waitcnt lgkmcnt(0)
	v_max3_f32 v33, v98, v32, v33
	v_sub_f32_e32 v34, v34, v33
	v_sub_f32_e32 v32, v98, v33
	v_sub_f32_e32 v98, v116, v33
	v_sub_f32_e32 v116, v117, v33
	v_exp_f32_e32 v117, v34
	v_sub_f32_e32 v34, v35, v33
	v_exp_f32_e32 v119, v34
	v_sub_f32_e32 v34, v36, v33
	v_exp_f32_e32 v120, v34
	v_sub_f32_e32 v34, v37, v33
	v_exp_f32_e32 v121, v34
	v_sub_f32_e32 v34, v38, v33
	v_exp_f32_e32 v38, v34
	v_sub_f32_e32 v34, v39, v33
	v_exp_f32_e32 v39, v34
	v_sub_f32_e32 v34, v40, v33
	v_exp_f32_e32 v40, v34
	v_sub_f32_e32 v34, v41, v33
	v_exp_f32_e32 v41, v34
	v_sub_f32_e32 v34, v42, v33
	v_exp_f32_e32 v42, v34
	v_sub_f32_e32 v34, v43, v33
	v_exp_f32_e32 v32, v32
	v_exp_f32_e32 v98, v98
	v_exp_f32_e32 v116, v116
	v_exp_f32_e32 v43, v34
	v_sub_f32_e32 v34, v44, v33
	v_exp_f32_e32 v44, v34
	v_sub_f32_e32 v34, v45, v33
	v_exp_f32_e32 v45, v34
	v_sub_f32_e32 v34, v46, v33
	v_exp_f32_e32 v46, v34
	v_sub_f32_e32 v34, v47, v33
	v_exp_f32_e32 v47, v34
	v_cvt_pk_bf16_f32 v34, v98, v116
	v_fmac_f32_e32 v98, v97, v32
	v_pk_mul_f32 v[16:17], v[16:17], v[32:33] op_sel_hi:[1,0]
	v_pk_mul_f32 v[0:1], v[0:1], v[32:33] op_sel_hi:[1,0]
	v_pk_mul_f32 v[18:19], v[18:19], v[32:33] op_sel_hi:[1,0]
	v_pk_mul_f32 v[2:3], v[2:3], v[32:33] op_sel_hi:[1,0]
	v_pk_mul_f32 v[20:21], v[20:21], v[32:33] op_sel_hi:[1,0]
	v_pk_mul_f32 v[4:5], v[4:5], v[32:33] op_sel_hi:[1,0]
	v_pk_mul_f32 v[22:23], v[22:23], v[32:33] op_sel_hi:[1,0]
	v_pk_mul_f32 v[6:7], v[6:7], v[32:33] op_sel_hi:[1,0]
	v_pk_mul_f32 v[24:25], v[24:25], v[32:33] op_sel_hi:[1,0]
	v_pk_mul_f32 v[8:9], v[8:9], v[32:33] op_sel_hi:[1,0]
	v_pk_mul_f32 v[26:27], v[26:27], v[32:33] op_sel_hi:[1,0]
	v_pk_mul_f32 v[10:11], v[10:11], v[32:33] op_sel_hi:[1,0]
	v_pk_mul_f32 v[28:29], v[28:29], v[32:33] op_sel_hi:[1,0]
	v_pk_mul_f32 v[12:13], v[12:13], v[32:33] op_sel_hi:[1,0]
	v_pk_mul_f32 v[30:31], v[30:31], v[32:33] op_sel_hi:[1,0]
	v_pk_mul_f32 v[14:15], v[14:15], v[32:33] op_sel_hi:[1,0]
	v_add_f32_e32 v32, v116, v98
	v_add_f32_e32 v32, v117, v32
	v_add_f32_e32 v32, v119, v32
	v_add_f32_e32 v32, v120, v32
	v_add_f32_e32 v32, v121, v32
	v_add_f32_e32 v32, v38, v32
	v_cvt_pk_bf16_f32 v35, v117, v119
	v_cvt_pk_bf16_f32 v36, v120, v121
	v_cvt_pk_bf16_f32 v37, v38, v39
	v_add_f32_e32 v32, v39, v32
	v_add_f32_e32 v32, v40, v32
	v_mfma_f32_32x32x16_bf16 v[16:31], v[60:63], v[34:37], v[16:31]
	v_add_f32_e32 v32, v41, v32
	v_add_f32_e32 v32, v42, v32
	v_add_f32_e32 v32, v43, v32
	v_add_f32_e32 v32, v44, v32
	v_add_f32_e32 v32, v45, v32
	v_add_f32_e32 v32, v46, v32
	v_add_f32_e32 v32, v47, v32
	v_mfma_f32_32x32x16_bf16 v[0:15], v[56:59], v[34:37], v[0:15]
	v_cvt_pk_bf16_f32 v34, v40, v41
	v_cvt_pk_bf16_f32 v35, v42, v43
	v_cvt_pk_bf16_f32 v36, v44, v45
	v_cvt_pk_bf16_f32 v37, v46, v47
	s_nop 1
	v_mfma_f32_32x32x16_bf16 v[16:31], v[48:51], v[34:37], v[16:31]
	v_mfma_f32_32x32x16_bf16 v[0:15], v[52:55], v[34:37], v[0:15]
	ds_bpermute_b32 v34, v118, v32
	s_waitcnt lgkmcnt(0)
	v_add_f32_e32 v34, v32, v34
	v_div_scale_f32 v32, s[2:3], v34, v34, 1.0
	v_rcp_f32_e32 v35, v32
	s_lshr_b32 s2, 0x2000, s31
	s_add_i32 s2, s2, -1
	v_fma_f32 v36, -v32, v35, 1.0
	v_fmac_f32_e32 v35, v36, v35
	v_div_scale_f32 v36, vcc, 1.0, v34, 1.0
	v_mul_f32_e32 v37, v36, v35
	v_fma_f32 v38, -v32, v37, v36
	v_fmac_f32_e32 v37, v38, v35
	v_fma_f32 v32, -v32, v37, v36
	v_div_fmas_f32 v32, v32, v35, v37
	v_div_fixup_f32 v32, v32, v34, 1.0
	v_pk_mul_f32 v[16:17], v[16:17], v[32:33] op_sel_hi:[1,0]
	v_pk_mul_f32 v[0:1], v[0:1], v[32:33] op_sel_hi:[1,0]
	v_pk_mul_f32 v[18:19], v[18:19], v[32:33] op_sel_hi:[1,0]
	v_pk_mul_f32 v[2:3], v[2:3], v[32:33] op_sel_hi:[1,0]
	v_pk_mul_f32 v[20:21], v[20:21], v[32:33] op_sel_hi:[1,0]
	v_pk_mul_f32 v[4:5], v[4:5], v[32:33] op_sel_hi:[1,0]
	v_pk_mul_f32 v[22:23], v[22:23], v[32:33] op_sel_hi:[1,0]
	v_pk_mul_f32 v[6:7], v[6:7], v[32:33] op_sel_hi:[1,0]
	v_pk_mul_f32 v[24:25], v[24:25], v[32:33] op_sel_hi:[1,0]
	v_pk_mul_f32 v[8:9], v[8:9], v[32:33] op_sel_hi:[1,0]
	v_pk_mul_f32 v[26:27], v[26:27], v[32:33] op_sel_hi:[1,0]
	v_pk_mul_f32 v[10:11], v[10:11], v[32:33] op_sel_hi:[1,0]
	v_pk_mul_f32 v[28:29], v[28:29], v[32:33] op_sel_hi:[1,0]
	v_pk_mul_f32 v[12:13], v[12:13], v[32:33] op_sel_hi:[1,0]
	v_pk_mul_f32 v[30:31], v[30:31], v[32:33] op_sel_hi:[1,0]
	v_pk_mul_f32 v[14:15], v[14:15], v[32:33] op_sel_hi:[1,0]
	v_log_f32_e32 v32, v34
	v_and_b32_e32 v34, s2, v132
	s_sub_i32 s2, 13, s31
	v_lshlrev_b32_e32 v34, s31, v34
	v_lshrrev_b32_e32 v35, s2, v132
	v_cvt_pk_bf16_f32 v0, v0, v1
	v_cvt_pk_bf16_f32 v1, v2, v3
	v_cvt_pk_bf16_f32 v3, v6, v7
	v_or_b32_e32 v6, v220, v99
	v_or_b32_e32 v34, v34, v35
	v_lshlrev_b32_e32 v6, 2, v6
	ds_bpermute_b32 v6, v6, v34
	v_cvt_pk_bf16_f32 v16, v16, v17
	v_cvt_pk_bf16_f32 v17, v18, v19
	v_cvt_pk_bf16_f32 v18, v20, v21
	v_cvt_pk_bf16_f32 v19, v22, v23
	s_waitcnt lgkmcnt(0)
	v_ashrrev_i32_e32 v7, 31, v6
	ds_write2_b64 v237, v[16:17], v[18:19] offset1:2
	v_cvt_pk_bf16_f32 v16, v24, v25
	v_cvt_pk_bf16_f32 v17, v26, v27
	v_cvt_pk_bf16_f32 v18, v28, v29
	v_cvt_pk_bf16_f32 v19, v30, v31
	v_cvt_pk_bf16_f32 v2, v4, v5
	v_lshl_add_u64 v[4:5], s[76:77], 1, v[174:175]
	v_lshl_add_u64 v[6:7], s[34:35], 0, v[6:7]
	ds_write2_b64 v237, v[16:17], v[18:19] offset0:4 offset1:6
	ds_write2_b64 v237, v[0:1], v[2:3] offset0:8 offset1:10
	v_cvt_pk_bf16_f32 v0, v8, v9
	v_mad_u64_u32 v[8:9], s[2:3], v6, s82, v[4:5]
	v_or_b32_e32 v6, v221, v99
	v_cvt_pk_bf16_f32 v1, v10, v11
	v_cvt_pk_bf16_f32 v2, v12, v13
	v_cvt_pk_bf16_f32 v3, v14, v15
	v_lshlrev_b32_e32 v6, 2, v6
	ds_write2_b64 v237, v[0:1], v[2:3] offset0:12 offset1:14
	ds_bpermute_b32 v6, v6, v34
	s_waitcnt lgkmcnt(0)
	v_add_u32_e32 v0, v218, v219
	ds_read_b128 v[0:3], v0
	v_mad_i32_i24 v9, v7, s82, v9
	s_waitcnt lgkmcnt(1)
	v_ashrrev_i32_e32 v7, 31, v6
	v_lshl_add_u64 v[6:7], s[34:35], 0, v[6:7]
	v_ashrrev_i32_e32 v35, 31, v34
	s_waitcnt lgkmcnt(0)
	global_store_dwordx4 v[8:9], v[0:3], off
	v_mad_u64_u32 v[8:9], s[2:3], v6, s82, v[4:5]
	v_or_b32_e32 v6, v222, v99
	v_lshlrev_b32_e32 v6, 2, v6
	ds_bpermute_b32 v6, v6, v34
	ds_read_b128 v[0:3], v238
	v_mad_i32_i24 v9, v7, s82, v9
	s_ashr_i32 s31, s30, 31
	s_and_b64 vcc, exec, s[36:37]
	s_waitcnt lgkmcnt(1)
	v_ashrrev_i32_e32 v7, 31, v6
	v_lshl_add_u64 v[6:7], s[34:35], 0, v[6:7]
	s_waitcnt lgkmcnt(0)
	global_store_dwordx4 v[8:9], v[0:3], off
	v_mad_u64_u32 v[8:9], s[2:3], v6, s82, v[4:5]
	v_or_b32_e32 v6, v223, v99
	ds_read_b128 v[0:3], v238 offset:1152
	v_lshlrev_b32_e32 v6, 2, v6
	ds_bpermute_b32 v6, v6, v34
	v_mad_i32_i24 v9, v7, s82, v9
	s_waitcnt lgkmcnt(1)
	global_store_dwordx4 v[8:9], v[0:3], off
	ds_read_b128 v[0:3], v238 offset:2304
	s_waitcnt lgkmcnt(1)
	v_ashrrev_i32_e32 v7, 31, v6
	v_lshl_add_u64 v[6:7], s[34:35], 0, v[6:7]
	v_mad_u64_u32 v[4:5], s[2:3], v6, s82, v[4:5]
	v_mad_i32_i24 v5, v7, s82, v5
	s_waitcnt lgkmcnt(0)
	global_store_dwordx4 v[4:5], v[0:3], off
	v_add_f32_e32 v4, v33, v32
	s_nop 0
	v_lshl_add_u64 v[0:1], s[34:35], 0, v[34:35]
	v_mad_u64_u32 v[2:3], s[2:3], v0, 48, s[28:29]
	v_mad_i32_i24 v3, v1, 48, v3
	v_lshl_add_u64 v[0:1], s[30:31], 2, v[2:3]
	global_store_dword v[0:1], v4, off
	s_cbranch_vccnz .LBB0_883
.LBB0_848:
	s_ashr_i32 s2, s85, 5
	s_mul_hi_i32 s3, s2, 0x2aaaaaab
	s_lshr_b32 s30, s3, 31
	s_lshr_b32 s3, s3, 1
	s_add_i32 s3, s3, s30
	s_mul_i32 s3, s3, 12
	s_sub_i32 s30, s2, s3
	s_mul_hi_i32 s2, s85, 0x2aaaaaab
	s_lshr_b32 s3, s2, 31
	s_ashr_i32 s2, s2, 6
	s_add_i32 s2, s2, s3
	s_and_b32 s87, s33, 62
	s_ashr_i32 s3, s2, 31
	s_lshl_b64 s[34:35], s[2:3], 13
	s_lshl_b32 s86, s87, 7
	s_or_b32 s2, s34, s86
	s_mov_b32 s3, s35
	v_lshl_add_u64 v[0:1], s[2:3], 0, v[164:165]
	v_mov_b64_e32 v[2:3], s[24:25]
	v_mad_u64_u32 v[2:3], s[2:3], v0, s82, v[2:3]
	s_lshl_b32 s76, s30, 6
	v_mad_i32_i24 v3, v1, s82, v3
	s_ashr_i32 s77, s76, 31
	v_lshl_add_u64 v[0:1], s[76:77], 1, v[2:3]
	v_lshl_add_u64 v[0:1], v[166:167], 1, v[0:1]
	global_load_dwordx4 v[128:131], v[0:1], off
	global_load_dwordx4 v[124:127], v[0:1], off offset:32
	global_load_dwordx4 v[116:119], v[0:1], off offset:64
	global_load_dwordx4 v[120:123], v[0:1], off offset:96
	s_waitcnt lgkmcnt(0)
	s_barrier
	s_waitcnt vmcnt(4)
	ds_write_b128 v224, v[64:67]
	ds_write_b128 v225, v[68:71] offset:55296
	ds_write_b128 v226, v[72:75]
	ds_write_b128 v227, v[76:79] offset:55296
	ds_write_b128 v228, v[80:83]
	ds_write_b128 v229, v[84:87] offset:55296
	ds_write_b128 v230, v[88:91]
	ds_write_b128 v231, v[92:95] offset:55296
	ds_write_b128 v232, v[100:103]
	ds_write_b128 v233, v[104:107] offset:55296
	ds_write_b128 v234, v[108:111]
	ds_write_b128 v235, v[112:115] offset:55296
	s_add_i32 s85, s85, s22
	s_waitcnt vmcnt(0)
	s_waitcnt lgkmcnt(0)
	s_barrier
	s_cmpk_gt_i32 s85, 0x5ff
	s_cselect_b64 s[36:37], -1, 0
	s_and_b64 vcc, exec, s[36:37]
	s_cbranch_vccnz .LBB0_874
	s_ashr_i32 s2, s85, 5
	s_mul_hi_i32 s3, s2, 0x2aaaaaab
	s_lshr_b32 s31, s3, 31
	s_lshr_b32 s3, s3, 1
	s_add_i32 s3, s3, s31
	s_mul_i32 s3, s3, 12
	s_sub_i32 s31, s2, s3
	s_mul_hi_i32 s2, s85, 0x2aaaaaab
	s_lshr_b32 s3, s2, 31
	s_ashr_i32 s2, s2, 6
	s_add_i32 vcc_lo, s2, s3
	s_ashr_i32 s2, s31, 1
	s_and_b32 s2, s2, -2
	s_add_i32 s3, s83, s33
	s_lshr_b32 s2, 64, s2
	s_and_b32 s80, s3, 62
	s_add_i32 s2, s2, -1
	s_and_b32 s2, s2, s80
	s_cmp_lg_u32 s2, 0
	s_cselect_b64 s[2:3], -1, 0
	s_ashr_i32 vcc_hi, vcc_lo, 31
	s_lshl_b64 s[78:79], vcc, 13
	s_lshl_b32 vcc_hi, s80, 7
	s_add_i32 s80, vcc_hi, 0xffffff80
	s_ashr_i32 s81, s80, 31
	s_add_u32 s78, s78, s80
	s_addc_u32 s79, s79, s81
	s_lshl_b32 s80, s31, 6
	s_ashr_i32 s81, s80, 31
	v_lshl_add_u64 v[0:1], s[80:81], 1, v[172:173]
	v_readlane_b32 s80, v250, 15
	v_mov_b32_e32 v68, v96
	v_mov_b32_e32 v69, v96
	v_readlane_b32 s81, v250, 16
	v_mov_b32_e32 v70, v96
	v_mov_b32_e32 v71, v96
	v_mov_b64_e32 v[64:65], v[68:69]
	s_or_b64 s[88:89], s[2:3], s[80:81]
	v_mov_b64_e32 v[66:67], v[70:71]
	s_and_saveexec_b64 s[80:81], s[88:89]
	s_cbranch_execz .LBB0_851
	v_lshl_add_u64 v[2:3], s[78:79], 0, v[176:177]
	v_mad_u64_u32 v[4:5], s[88:89], v2, s82, v[0:1]
	v_mad_i32_i24 v5, v3, s82, v5
	global_load_dwordx4 v[64:67], v[4:5], off nt

.LBB0_874:
	s_ashr_i32 s2, s30, 1
	s_and_b32 s31, s2, -2
	s_lshr_b32 s2, 64, s31
	s_add_i32 s2, s2, -1
	s_and_b32 s78, s2, s87
	s_cmp_lg_u32 s78, 0
	s_cselect_b64 s[2:3], -1, 0
	s_cmp_eq_u32 s78, 0
	s_cselect_b64 s[78:79], -1, 0
	s_or_b64 s[80:81], s[6:7], s[2:3]
	s_andn2_b64 vcc, exec, s[80:81]
	s_cbranch_vccnz .LBB0_878
	ds_read_b128 v[0:3], v239
	ds_read_b128 v[16:19], v239 offset:32
	ds_read_b128 v[20:23], v239 offset:64
	ds_read_b128 v[24:27], v239 offset:96
	ds_read_b128 v[28:31], v239 offset:4608
	ds_read_b128 v[48:51], v239 offset:4640
	ds_read_b128 v[52:55], v239 offset:4672
	ds_read_b128 v[56:59], v239 offset:4704
	s_waitcnt lgkmcnt(7)
	v_mfma_f32_32x32x16_bf16 v[0:15], v[0:3], v[128:131], 0
	v_readlane_b32 s80, v251, 22
	v_readlane_b32 s81, v251, 23
	s_andn2_b64 vcc, exec, s[78:79]
	s_waitcnt lgkmcnt(6)
	v_mfma_f32_32x32x16_bf16 v[0:15], v[16:19], v[124:127], v[0:15]
	s_waitcnt lgkmcnt(5)
	v_mfma_f32_32x32x16_bf16 v[0:15], v[20:23], v[116:119], v[0:15]
	s_waitcnt lgkmcnt(4)
	v_mfma_f32_32x32x16_bf16 v[0:15], v[24:27], v[120:123], v[0:15]
	s_waitcnt lgkmcnt(3)
	v_mfma_f32_32x32x16_bf16 v[32:47], v[28:31], v[128:131], 0
	s_nop 9
	v_cndmask_b32_e64 v20, v1, v240, s[80:81]
	v_readlane_b32 s80, v251, 52
	v_readlane_b32 s81, v251, 53
	v_cndmask_b32_e64 v0, v0, v240, s[4:5]
	s_nop 0
	v_cndmask_b32_e64 v21, v2, v240, s[80:81]
	v_readlane_b32 s80, v251, 54
	s_waitcnt lgkmcnt(2)
	v_mfma_f32_32x32x16_bf16 v[32:47], v[48:51], v[124:127], v[32:47]
	v_readlane_b32 s81, v251, 55
	s_nop 1
	v_cndmask_b32_e64 v22, v3, v240, s[80:81]
	v_readlane_b32 s80, v251, 56
	v_readlane_b32 s81, v251, 57
	s_waitcnt lgkmcnt(1)
	v_mfma_f32_32x32x16_bf16 v[32:47], v[52:55], v[116:119], v[32:47]
	v_cndmask_b32_e64 v23, v4, v240, s[80:81]
	v_readlane_b32 s80, v251, 58
	v_readlane_b32 s81, v251, 59
	s_nop 1
	v_cndmask_b32_e64 v5, v5, v240, s[80:81]
	v_readlane_b32 s80, v251, 60
	v_readlane_b32 s81, v251, 61
	s_waitcnt lgkmcnt(0)
	v_mfma_f32_32x32x16_bf16 v[32:47], v[56:59], v[120:123], v[32:47]
	ds_read_b128 v[16:19], v169 offset:55296
	ds_read_b128 v[132:135], v169 offset:55328
	ds_read_b128 v[140:143], v236 offset:55296
	ds_read_b128 v[136:139], v236 offset:55328
	ds_read_b128 v[60:63], v169 offset:55360
	ds_read_b128 v[56:59], v236 offset:55360
	ds_read_b128 v[52:55], v169 offset:55392
	ds_read_b128 v[48:51], v236 offset:55392
	v_cndmask_b32_e64 v6, v6, v240, s[80:81]
	v_readlane_b32 s80, v251, 62
	v_readlane_b32 s81, v251, 63
	s_nop 1
	v_cndmask_b32_e64 v7, v7, v240, s[80:81]
	v_readlane_b32 s80, v250, 0
	v_readlane_b32 s81, v250, 1
	s_nop 1
	v_cndmask_b32_e64 v8, v8, v240, s[80:81]
	v_readlane_b32 s80, v251, 20
	v_readlane_b32 s81, v251, 21
	s_nop 1
	v_cndmask_b32_e64 v9, v9, v240, s[80:81]
	v_readlane_b32 s80, v250, 2
	v_readlane_b32 s81, v250, 3
	s_nop 1
	v_cndmask_b32_e64 v10, v10, v240, s[80:81]
	v_readlane_b32 s80, v250, 5
	v_readlane_b32 s81, v250, 6
	s_nop 1
	v_cndmask_b32_e64 v1, v11, v240, s[80:81]
	v_readlane_b32 s80, v250, 7
	v_readlane_b32 s81, v250, 8
	s_nop 1
	v_cndmask_b32_e64 v2, v12, v240, s[80:81]
	v_readlane_b32 s80, v250, 9
	v_readlane_b32 s81, v250, 10
	s_nop 1
	v_cndmask_b32_e64 v3, v13, v240, s[80:81]
	v_readlane_b32 s80, v250, 11
	v_readlane_b32 s81, v250, 12
	s_nop 1
	v_cndmask_b32_e64 v4, v14, v240, s[80:81]
	v_readlane_b32 s80, v250, 13
	v_readlane_b32 s81, v250, 14
	s_nop 1
	v_cndmask_b32_e64 v97, v15, v240, s[80:81]
	s_cbranch_vccnz .LBB0_877
	v_cndmask_b32_e64 v0, v0, v240, s[38:39]
	v_cndmask_b32_e64 v20, v20, v240, s[38:39]
	v_cndmask_b32_e64 v21, v21, v240, s[38:39]
	v_cndmask_b32_e64 v22, v22, v240, s[38:39]
	v_cndmask_b32_e64 v23, v23, v240, s[38:39]
	v_cndmask_b32_e64 v5, v5, v240, s[38:39]
	v_cndmask_b32_e64 v6, v6, v240, s[38:39]
	v_cndmask_b32_e64 v7, v7, v240, s[38:39]
	v_cndmask_b32_e64 v8, v8, v240, s[38:39]
	v_cndmask_b32_e64 v9, v9, v240, s[38:39]
	v_cndmask_b32_e64 v10, v10, v240, s[38:39]
	v_cndmask_b32_e64 v1, v1, v240, s[38:39]
	v_cndmask_b32_e64 v2, v2, v240, s[38:39]
	v_cndmask_b32_e64 v3, v3, v240, s[38:39]
	v_cndmask_b32_e64 v4, v4, v240, s[38:39]
	v_cndmask_b32_e64 v97, v97, v240, s[38:39]
	v_cndmask_b32_e64 v32, v32, v240, s[40:41]
	v_cndmask_b32_e64 v33, v33, v240, s[40:41]
	v_cndmask_b32_e64 v34, v34, v240, s[40:41]
	v_cndmask_b32_e64 v35, v35, v240, s[40:41]
	v_cndmask_b32_e64 v36, v36, v240, s[40:41]
	v_cndmask_b32_e64 v37, v37, v240, s[40:41]
	v_cndmask_b32_e64 v38, v38, v240, s[40:41]
	v_cndmask_b32_e64 v39, v39, v240, s[40:41]
	v_cndmask_b32_e64 v40, v40, v240, s[40:41]
	v_cndmask_b32_e64 v41, v41, v240, s[40:41]
	v_cndmask_b32_e64 v42, v42, v240, s[40:41]
	v_cndmask_b32_e64 v43, v43, v240, s[40:41]
	v_cndmask_b32_e64 v44, v44, v240, s[40:41]
	v_cndmask_b32_e64 v45, v45, v240, s[40:41]
	v_cndmask_b32_e64 v46, v46, v240, s[40:41]
	v_cndmask_b32_e64 v47, v47, v240, s[40:41]

.LBB0_880:
	s_andn2_b64 vcc, exec, s[2:3]
	s_cbranch_vccnz .LBB0_847
	ds_read_b128 v[32:35], v239 offset:9216
	ds_read_b128 v[132:135], v239 offset:9248
	ds_read_b128 v[136:139], v239 offset:9280
	ds_read_b128 v[140:143], v239 offset:9312
	ds_read_b128 v[36:39], v239 offset:13824
	ds_read_b128 v[144:147], v239 offset:13856
	ds_read_b128 v[148:151], v239 offset:13888
	ds_read_b128 v[152:155], v239 offset:13920
	s_waitcnt lgkmcnt(7)
	v_mfma_f32_32x32x16_bf16 v[48:63], v[32:35], v[128:131], 0
	s_andn2_b64 vcc, exec, s[78:79]
	s_waitcnt lgkmcnt(3)
	v_mfma_f32_32x32x16_bf16 v[32:47], v[36:39], v[128:131], 0
	v_mfma_f32_32x32x16_bf16 v[48:63], v[132:135], v[124:127], v[48:63]
	s_waitcnt lgkmcnt(2)
	v_mfma_f32_32x32x16_bf16 v[32:47], v[144:147], v[124:127], v[32:47]
	v_mfma_f32_32x32x16_bf16 v[48:63], v[136:139], v[116:119], v[48:63]
	s_waitcnt lgkmcnt(1)
	v_mfma_f32_32x32x16_bf16 v[32:47], v[148:151], v[116:119], v[32:47]
	v_mfma_f32_32x32x16_bf16 v[48:63], v[140:143], v[120:123], v[48:63]
	s_waitcnt lgkmcnt(0)
	v_mfma_f32_32x32x16_bf16 v[32:47], v[152:155], v[120:123], v[32:47]
	ds_read_b128 v[160:163], v171
	ds_read_b128 v[156:159], v171 offset:25088
	ds_read_b128 v[148:151], v212
	ds_read_b128 v[152:155], v212 offset:25088
	ds_read_b128 v[144:147], v213
	ds_read_b128 v[140:143], v213 offset:25088
	ds_read_b128 v[136:139], v214
	ds_read_b128 v[132:135], v214 offset:25088
	s_cbranch_vccnz .LBB0_846
	s_nop 0
	v_cndmask_b32_e64 v48, v48, v240, s[42:43]
	v_cndmask_b32_e64 v49, v49, v240, s[42:43]
	v_cndmask_b32_e64 v50, v50, v240, s[42:43]
	v_cndmask_b32_e64 v51, v51, v240, s[42:43]
	v_cndmask_b32_e64 v52, v52, v240, s[42:43]
	v_cndmask_b32_e64 v53, v53, v240, s[42:43]
	v_cndmask_b32_e64 v54, v54, v240, s[42:43]
	v_cndmask_b32_e64 v55, v55, v240, s[42:43]
	v_cndmask_b32_e64 v56, v56, v240, s[42:43]
	v_cndmask_b32_e64 v57, v57, v240, s[42:43]
	v_cndmask_b32_e64 v58, v58, v240, s[42:43]
	v_cndmask_b32_e64 v59, v59, v240, s[42:43]
	v_cndmask_b32_e64 v60, v60, v240, s[42:43]
	v_cndmask_b32_e64 v61, v61, v240, s[42:43]
	v_cndmask_b32_e64 v62, v62, v240, s[42:43]
	v_cndmask_b32_e64 v63, v63, v240, s[42:43]
	v_cndmask_b32_e64 v32, v32, v240, s[44:45]
	v_cndmask_b32_e64 v33, v33, v240, s[44:45]
	v_cndmask_b32_e64 v34, v34, v240, s[44:45]
	v_cndmask_b32_e64 v35, v35, v240, s[44:45]
	v_cndmask_b32_e64 v36, v36, v240, s[44:45]
	v_cndmask_b32_e64 v37, v37, v240, s[44:45]
	v_cndmask_b32_e64 v38, v38, v240, s[44:45]
	v_cndmask_b32_e64 v39, v39, v240, s[44:45]
	v_cndmask_b32_e64 v40, v40, v240, s[44:45]
	v_cndmask_b32_e64 v41, v41, v240, s[44:45]
	v_cndmask_b32_e64 v42, v42, v240, s[44:45]
	v_cndmask_b32_e64 v43, v43, v240, s[44:45]
	v_cndmask_b32_e64 v44, v44, v240, s[44:45]
	v_cndmask_b32_e64 v45, v45, v240, s[44:45]
	v_cndmask_b32_e64 v46, v46, v240, s[44:45]
	v_cndmask_b32_e64 v47, v47, v240, s[44:45]
	s_branch .LBB0_846
